# adds: P6 merge epilogue software-pipelined (6 row-groups of loads in flight); P2 EpiQ loop prefetches next iteration (x2 unroll); attention max-tree/row-sum trims, 5 V-fragment LDS reads issued before
# speedup vs baseline: 1.0339x; 1.0064x over previous
.LBB0_428:
	v_mov_b32_e32 v133, v191
	s_waitcnt vmcnt(0)
	s_barrier
	s_lshl_b32 s4, s73, 6
	v_and_or_b32 v138, v133, 15, s74
	v_and_b32_e32 v133, 48, v133
	s_add_i32 s4, s4, 0
	v_mul_lo_u32 v138, v138, s56
	v_add3_u32 v133, s4, v133, v138
	v_cvt_pk_bf16_f32 v4, v4, v5
	v_cvt_pk_bf16_f32 v5, v6, v7
	v_cvt_pk_bf16_f32 v6, v0, v1
	v_cvt_pk_bf16_f32 v7, v2, v3
	v_add_u32_e32 v0, 0x16c00, v133
	ds_write_b128 v0, v[4:7]
	v_lshl_or_b32 v0, s71, 8, v135
	v_mul_hi_i32 v1, v0, s58
	v_lshrrev_b32_e32 v2, 31, v1
	v_lshrrev_b32_e32 v1, 4, v1
	v_add_u32_e32 v1, v1, v2
	v_mul_lo_u32 v1, v1, s64
	v_sub_u32_e32 v4, v0, v1
	v_cmp_gt_u32_e64 s[6:7], s65, v4
	v_cvt_pk_bf16_f32 v28, v28, v29
	v_cvt_pk_bf16_f32 v29, v30, v31
	v_cndmask_b32_e64 v0, -2, 2, s[6:7]
	v_add_u32_e32 v0, v0, v131
	v_cvt_pk_bf16_f32 v31, v26, v27
	v_lshl_add_u32 v26, v0, 4, v150
	v_mad_i64_i32 v[0:1], s[10:11], s0, v154, v[128:129]
	v_cvt_pk_bf16_f32 v52, v52, v53
	v_cvt_pk_bf16_f32 v53, v54, v55
	v_cvt_pk_bf16_f32 v54, v48, v49
	v_cvt_pk_bf16_f32 v55, v50, v51
	v_add_u32_e32 v48, 0x10900, v133
	v_cvt_pk_bf16_f32 v36, v36, v37
	v_cvt_pk_bf16_f32 v37, v38, v39
	v_cvt_pk_bf16_f32 v38, v32, v33
	v_cvt_pk_bf16_f32 v39, v34, v35
	v_add_u32_e32 v32, 0x12a00, v133
	v_cvt_pk_bf16_f32 v20, v20, v21
	v_cvt_pk_bf16_f32 v21, v22, v23
	v_cvt_pk_bf16_f32 v22, v16, v17
	v_cvt_pk_bf16_f32 v23, v18, v19
	v_add_u32_e32 v16, 0x14b00, v133
	v_lshl_or_b32 v2, s70, 8, v135
	s_lshl_b32 s10, s69, 8
	v_cvt_pk_bf16_f32 v124, v124, v125
	v_cvt_pk_bf16_f32 v125, v126, v127
	v_cvt_pk_bf16_f32 v126, v120, v121
	v_cvt_pk_bf16_f32 v127, v122, v123
	v_cvt_pk_bf16_f32 v116, v116, v117
	v_cvt_pk_bf16_f32 v117, v118, v119
	v_cvt_pk_bf16_f32 v118, v112, v113
	v_cvt_pk_bf16_f32 v119, v114, v115
	v_cvt_pk_bf16_f32 v108, v108, v109
	v_cvt_pk_bf16_f32 v109, v110, v111
	v_cvt_pk_bf16_f32 v110, v104, v105
	v_cvt_pk_bf16_f32 v111, v106, v107
	v_cvt_pk_bf16_f32 v100, v100, v101
	v_cvt_pk_bf16_f32 v101, v102, v103
	v_cvt_pk_bf16_f32 v102, v96, v97
	v_cvt_pk_bf16_f32 v103, v98, v99
	v_cvt_pk_bf16_f32 v92, v92, v93
	v_cvt_pk_bf16_f32 v93, v94, v95
	v_cvt_pk_bf16_f32 v94, v88, v89
	v_cvt_pk_bf16_f32 v95, v90, v91
	v_cvt_pk_bf16_f32 v84, v84, v85
	v_cvt_pk_bf16_f32 v85, v86, v87
	v_cvt_pk_bf16_f32 v86, v80, v81
	v_cvt_pk_bf16_f32 v87, v82, v83
	v_cvt_pk_bf16_f32 v76, v76, v77
	v_cvt_pk_bf16_f32 v77, v78, v79
	v_cvt_pk_bf16_f32 v78, v72, v73
	v_cvt_pk_bf16_f32 v79, v74, v75
	v_cvt_pk_bf16_f32 v68, v68, v69
	v_cvt_pk_bf16_f32 v69, v70, v71
	v_cvt_pk_bf16_f32 v70, v64, v65
	v_cvt_pk_bf16_f32 v71, v66, v67
	v_add_u32_e32 v64, 0x10800, v133
	v_cvt_pk_bf16_f32 v60, v60, v61
	v_cvt_pk_bf16_f32 v61, v62, v63
	v_cvt_pk_bf16_f32 v62, v56, v57
	v_cvt_pk_bf16_f32 v63, v58, v59
	ds_write_b128 v48, v[52:55]
	v_add_u32_e32 v48, 0x12900, v133
	v_cvt_pk_bf16_f32 v44, v44, v45
	v_cvt_pk_bf16_f32 v45, v46, v47
	v_cvt_pk_bf16_f32 v46, v40, v41
	v_cvt_pk_bf16_f32 v47, v42, v43
	ds_write_b128 v32, v[36:39]
	v_add_u32_e32 v32, 0x14a00, v133
	v_cvt_pk_bf16_f32 v30, v24, v25
	ds_write_b128 v16, v[20:23]
	v_add_u32_e32 v16, 0x16b00, v133
	v_cvt_pk_bf16_f32 v12, v12, v13
	v_cvt_pk_bf16_f32 v13, v14, v15
	v_cvt_pk_bf16_f32 v14, v8, v9
	v_cvt_pk_bf16_f32 v15, v10, v11
	v_subrev_u32_e32 v2, s10, v2
	ds_write_b128 v133, v[124:127]
	ds_write_b128 v133, v[116:119] offset:256
	ds_write_b128 v133, v[108:111] offset:8448
	ds_write_b128 v133, v[100:103] offset:8704
	ds_write_b128 v133, v[92:95] offset:16896
	ds_write_b128 v133, v[84:87] offset:17152
	ds_write_b128 v133, v[76:79] offset:25344
	ds_write_b128 v133, v[68:71] offset:25600
	ds_write_b128 v64, v[60:63]
	ds_write_b128 v48, v[44:47]
	ds_write_b128 v32, v[28:31]
	ds_write_b128 v16, v[12:15]
	v_ashrrev_i32_e32 v3, 31, v2
	s_waitcnt lgkmcnt(0)
	s_barrier
	v_lshl_add_u64 v[20:21], v[2:3], 1, v[0:1]
	s_lshl_b64 s[10:11], s[0:1], 12
	s_lshl_b64 s[0:1], s[0:1], 14
	v_lshlrev_b32_e32 v2, 2, v4
	v_mov_b32_e32 v1, s1
	v_or_b32_e32 v0, s0, v134
	v_and_b32_e32 v2, 32, v2
	v_mov_b32_e32 v3, v132
	v_cmp_gt_i32_e64 s[4:5], 64, v4
	v_mov_b32_e32 v23, s11
	v_or_b32_e32 v22, s10, v130
	v_lshl_add_u64 v[24:25], v[0:1], 0, v[2:3]
	s_mov_b32 s28, 0
	v_add_u32_e32 v80, 0x2c00000, v22
	v_add_u32_e32 v81, 0x2c80000, v22
	v_add_u32_e32 v82, 0x2d00000, v22
	v_add_u32_e32 v83, 0x2a00000, v24
	v_add_u32_e32 v84, 0x2800000, v24
	global_load_dwordx4 v[12:15], v80, s[26:27]
	global_load_dwordx4 v[16:19], v81, s[26:27]
	global_load_dwordx4 v[8:11], v82, s[26:27]
	global_load_dwordx4 v[28:31], v83, s[26:27]
	global_load_dwordx4 v[32:35], v83, s[26:27] offset:16
	global_load_dwordx4 v[36:39], v84, s[26:27]
	global_load_dwordx4 v[40:43], v84, s[26:27] offset:16
	v_add_u32_e32 v22, 0x100, v22
	v_add_u32_e32 v24, 0x400, v24
	s_branch .LBB0_430
.LBB0_430:
	v_add_u32_e32 v80, 0x2c00000, v22
	v_add_u32_e32 v81, 0x2c80000, v22
	v_add_u32_e32 v82, 0x2d00000, v22
	v_add_u32_e32 v83, 0x2a00000, v24
	v_add_u32_e32 v84, 0x2800000, v24
	global_load_dwordx4 v[56:59], v80, s[26:27]
	global_load_dwordx4 v[60:63], v81, s[26:27]
	global_load_dwordx4 v[52:55], v82, s[26:27]
	global_load_dwordx4 v[64:67], v83, s[26:27]
	global_load_dwordx4 v[68:71], v83, s[26:27] offset:16
	global_load_dwordx4 v[72:75], v84, s[26:27]
	global_load_dwordx4 v[76:79], v84, s[26:27] offset:16
	v_add_u32_e32 v22, 0x100, v22
	v_add_u32_e32 v24, 0x400, v24
	v_add_u32_e32 v85, s28, v151
	ds_read_b128 v[4:7], v85
	v_add_u32_e32 v85, s28, v26
	ds_read_b128 v[44:47], v85
	s_waitcnt vmcnt(7)
	s_waitcnt lgkmcnt(0)
	v_lshlrev_b32_e32 v0, 16, v4
	v_and_b32_e32 v1, 0xffff0000, v4
	v_lshlrev_b32_e32 v2, 16, v5
	v_and_b32_e32 v3, 0xffff0000, v5
	v_lshlrev_b32_e32 v4, 16, v6
	v_and_b32_e32 v5, 0xffff0000, v6
	v_lshlrev_b32_e32 v6, 16, v7
	v_and_b32_e32 v7, 0xffff0000, v7
	v_lshlrev_b32_e32 v27, 16, v44
	v_and_b32_e32 v44, 0xffff0000, v44
	v_lshlrev_b32_e32 v48, 16, v45
	v_and_b32_e32 v45, 0xffff0000, v45
	v_lshlrev_b32_e32 v49, 16, v46
	v_and_b32_e32 v46, 0xffff0000, v46
	v_lshlrev_b32_e32 v50, 16, v47
	v_and_b32_e32 v47, 0xffff0000, v47
	s_and_saveexec_b64 s[0:1], s[4:5]
	s_xor_b64 s[0:1], exec, s[0:1]
	s_andn2_saveexec_b64 s[10:11], s[0:1]
	s_cbranch_execz .Lq_norota
	v_mul_f32_e32 v27, v28, v27
	v_mul_f32_e32 v29, v29, v44
	v_mul_f32_e32 v30, v30, v48
	v_mul_f32_e32 v31, v31, v45
	v_mul_f32_e32 v32, v32, v49
	v_mul_f32_e32 v33, v33, v46
	v_mul_f32_e32 v34, v34, v50
	v_mul_f32_e32 v35, v35, v47
	v_cndmask_b32_e64 v28, v27, -v27, s[6:7]
	v_cndmask_b32_e64 v29, v29, -v29, s[6:7]
	v_cndmask_b32_e64 v30, v30, -v30, s[6:7]
	v_cndmask_b32_e64 v31, v31, -v31, s[6:7]
	v_cndmask_b32_e64 v32, v32, -v32, s[6:7]
	v_cndmask_b32_e64 v33, v33, -v33, s[6:7]
	v_cndmask_b32_e64 v34, v34, -v34, s[6:7]
	v_cndmask_b32_e64 v35, v35, -v35, s[6:7]
	v_fmac_f32_e32 v28, v36, v0
	v_fmac_f32_e32 v29, v37, v1
	v_fmac_f32_e32 v30, v38, v2
	v_fmac_f32_e32 v31, v39, v3
	v_fmac_f32_e32 v32, v40, v4
	v_fmac_f32_e32 v33, v41, v5
	v_fmac_f32_e32 v34, v42, v6
	v_fmac_f32_e32 v35, v43, v7
	v_mov_b64_e32 v[0:1], v[28:29]
	v_mov_b64_e32 v[2:3], v[30:31]
	v_mov_b64_e32 v[4:5], v[32:33]
	v_mov_b64_e32 v[6:7], v[34:35]
.Lq_norota:
	s_or_b64 exec, exec, s[10:11]
	v_mov_b32_e32 v28, v13
	v_mov_b32_e32 v29, v14
	v_mov_b32_e32 v13, v15
	v_pk_add_f32 v[12:13], v[28:29], v[12:13]
	v_add_f32_e32 v14, v16, v17
	v_pk_add_f32 v[12:13], v[12:13], v[12:13] op_sel:[0,1] op_sel_hi:[1,0]
	v_add_f32_e32 v16, v18, v19
	v_mov_b32_e32 v13, v8
	v_mov_b32_e32 v133, v9
	v_mov_b32_e32 v15, v10
	v_mov_b32_e32 v17, v11
	v_pk_add_f32 v[8:9], v[12:13], v[132:133]
	v_pk_add_f32 v[10:11], v[14:15], v[16:17]
	v_pk_add_f32 v[8:9], v[8:9], v[10:11]
	v_add_f32_e32 v8, v8, v9
	v_fmamk_f32 v8, v8, 0x3b2aaaab, v152
	v_mul_f32_e32 v9, 0x4b800000, v8
	v_cmp_gt_f32_e32 vcc, s68, v8
	v_cndmask_b32_e32 v8, v8, v9, vcc
	v_rsq_f32_e32 v8, v8
	s_nop 0
	v_mul_f32_e32 v9, 0x45800000, v8
	v_cndmask_b32_e32 v8, v8, v9, vcc
	v_mul_f32_e32 v8, 0x3e16c740, v8
	v_pk_mul_f32 v[0:1], v[8:9], v[0:1] op_sel_hi:[0,1]
	v_pk_mul_f32 v[2:3], v[8:9], v[2:3] op_sel_hi:[0,1]
	v_pk_mul_f32 v[4:5], v[8:9], v[4:5] op_sel_hi:[0,1]
	v_pk_mul_f32 v[6:7], v[8:9], v[6:7] op_sel_hi:[0,1]
	v_cvt_pk_bf16_f32 v0, v0, v1
	v_cvt_pk_bf16_f32 v1, v2, v3
	v_cvt_pk_bf16_f32 v2, v4, v5
	v_cvt_pk_bf16_f32 v3, v6, v7
	v_lshl_add_u64 v[4:5], s[26:27], 0, v[20:21]
	v_lshl_add_u64 v[20:21], v[20:21], 0, s[46:47]
	global_store_dwordx4 v[4:5], v[0:3], off
	s_addk_i32 s28, 0x2100
	s_cmp_eq_u32 s28, 0x1ef00
	s_cbranch_scc1 .Lq_last
	v_add_u32_e32 v80, 0x2c00000, v22
	v_add_u32_e32 v81, 0x2c80000, v22
	v_add_u32_e32 v82, 0x2d00000, v22
	v_add_u32_e32 v83, 0x2a00000, v24
	v_add_u32_e32 v84, 0x2800000, v24
	global_load_dwordx4 v[12:15], v80, s[26:27]
	global_load_dwordx4 v[16:19], v81, s[26:27]
	global_load_dwordx4 v[8:11], v82, s[26:27]
	global_load_dwordx4 v[28:31], v83, s[26:27]
	global_load_dwordx4 v[32:35], v83, s[26:27] offset:16
	global_load_dwordx4 v[36:39], v84, s[26:27]
	global_load_dwordx4 v[40:43], v84, s[26:27] offset:16
	v_add_u32_e32 v22, 0x100, v22
	v_add_u32_e32 v24, 0x400, v24
	v_add_u32_e32 v85, s28, v151
	ds_read_b128 v[4:7], v85
	v_add_u32_e32 v85, s28, v26
	ds_read_b128 v[44:47], v85
	s_waitcnt vmcnt(7)
	s_branch .Lq_c2
.Lq_last:
	v_add_u32_e32 v85, s28, v151
	ds_read_b128 v[4:7], v85
	v_add_u32_e32 v85, s28, v26
	ds_read_b128 v[44:47], v85
	s_waitcnt vmcnt(0)
.Lq_c2:
	s_waitcnt lgkmcnt(0)
	v_lshlrev_b32_e32 v0, 16, v4
	v_and_b32_e32 v1, 0xffff0000, v4
	v_lshlrev_b32_e32 v2, 16, v5
	v_and_b32_e32 v3, 0xffff0000, v5
	v_lshlrev_b32_e32 v4, 16, v6
	v_and_b32_e32 v5, 0xffff0000, v6
	v_lshlrev_b32_e32 v6, 16, v7
	v_and_b32_e32 v7, 0xffff0000, v7
	v_lshlrev_b32_e32 v27, 16, v44
	v_and_b32_e32 v44, 0xffff0000, v44
	v_lshlrev_b32_e32 v48, 16, v45
	v_and_b32_e32 v45, 0xffff0000, v45
	v_lshlrev_b32_e32 v49, 16, v46
	v_and_b32_e32 v46, 0xffff0000, v46
	v_lshlrev_b32_e32 v50, 16, v47
	v_and_b32_e32 v47, 0xffff0000, v47
	s_and_saveexec_b64 s[0:1], s[4:5]
	s_xor_b64 s[0:1], exec, s[0:1]
	s_andn2_saveexec_b64 s[10:11], s[0:1]
	s_cbranch_execz .Lq_norotb
	v_mul_f32_e32 v27, v64, v27
	v_mul_f32_e32 v65, v65, v44
	v_mul_f32_e32 v66, v66, v48
	v_mul_f32_e32 v67, v67, v45
	v_mul_f32_e32 v68, v68, v49
	v_mul_f32_e32 v69, v69, v46
	v_mul_f32_e32 v70, v70, v50
	v_mul_f32_e32 v71, v71, v47
	v_cndmask_b32_e64 v64, v27, -v27, s[6:7]
	v_cndmask_b32_e64 v65, v65, -v65, s[6:7]
	v_cndmask_b32_e64 v66, v66, -v66, s[6:7]
	v_cndmask_b32_e64 v67, v67, -v67, s[6:7]
	v_cndmask_b32_e64 v68, v68, -v68, s[6:7]
	v_cndmask_b32_e64 v69, v69, -v69, s[6:7]
	v_cndmask_b32_e64 v70, v70, -v70, s[6:7]
	v_cndmask_b32_e64 v71, v71, -v71, s[6:7]
	v_fmac_f32_e32 v64, v72, v0
	v_fmac_f32_e32 v65, v73, v1
	v_fmac_f32_e32 v66, v74, v2
	v_fmac_f32_e32 v67, v75, v3
	v_fmac_f32_e32 v68, v76, v4
	v_fmac_f32_e32 v69, v77, v5
	v_fmac_f32_e32 v70, v78, v6
	v_fmac_f32_e32 v71, v79, v7
	v_mov_b64_e32 v[0:1], v[64:65]
	v_mov_b64_e32 v[2:3], v[66:67]
	v_mov_b64_e32 v[4:5], v[68:69]
	v_mov_b64_e32 v[6:7], v[70:71]
.Lq_norotb:
	s_or_b64 exec, exec, s[10:11]
	v_mov_b32_e32 v64, v57
	v_mov_b32_e32 v65, v58
	v_mov_b32_e32 v57, v59
	v_pk_add_f32 v[56:57], v[64:65], v[56:57]
	v_add_f32_e32 v58, v60, v61
	v_pk_add_f32 v[56:57], v[56:57], v[56:57] op_sel:[0,1] op_sel_hi:[1,0]
	v_add_f32_e32 v60, v62, v63
	v_mov_b32_e32 v57, v52
	v_mov_b32_e32 v133, v53
	v_mov_b32_e32 v59, v54
	v_mov_b32_e32 v61, v55
	v_pk_add_f32 v[52:53], v[56:57], v[132:133]
	v_pk_add_f32 v[54:55], v[58:59], v[60:61]
	v_pk_add_f32 v[52:53], v[52:53], v[54:55]
	v_add_f32_e32 v52, v52, v53
	v_fmamk_f32 v52, v52, 0x3b2aaaab, v152
	v_mul_f32_e32 v53, 0x4b800000, v52
	v_cmp_gt_f32_e32 vcc, s68, v52
	v_cndmask_b32_e32 v52, v52, v53, vcc
	v_rsq_f32_e32 v52, v52
	s_nop 0
	v_mul_f32_e32 v53, 0x45800000, v52
	v_cndmask_b32_e32 v52, v52, v53, vcc
	v_mul_f32_e32 v52, 0x3e16c740, v52
	v_pk_mul_f32 v[0:1], v[52:53], v[0:1] op_sel_hi:[0,1]
	v_pk_mul_f32 v[2:3], v[52:53], v[2:3] op_sel_hi:[0,1]
	v_pk_mul_f32 v[4:5], v[52:53], v[4:5] op_sel_hi:[0,1]
	v_pk_mul_f32 v[6:7], v[52:53], v[6:7] op_sel_hi:[0,1]
	v_cvt_pk_bf16_f32 v0, v0, v1
	v_cvt_pk_bf16_f32 v1, v2, v3
	v_cvt_pk_bf16_f32 v2, v4, v5
	v_cvt_pk_bf16_f32 v3, v6, v7
	v_lshl_add_u64 v[4:5], s[26:27], 0, v[20:21]
	v_lshl_add_u64 v[20:21], v[20:21], 0, s[46:47]
	global_store_dwordx4 v[4:5], v[0:3], off
	s_addk_i32 s28, 0x2100
	s_cmp_lg_u32 s28, 0x21000
	s_cbranch_scc1 .LBB0_430
	s_branch .LBB0_418

.LBB0_587:
	s_nop 8
	v_max3_f32 v143, v49, v65, v64
	v_max_f32_e32 v143, v143, v48
	v_max3_f32 v145, v66, v50, v67
	v_max3_f32 v143, v143, v145, v51
	v_max3_f32 v145, v68, v52, v69
	v_max3_f32 v143, v143, v145, v53
	v_max3_f32 v145, v70, v54, v71
	v_max3_f32 v143, v143, v145, v55
	v_max3_f32 v145, v72, v56, v73
	v_max3_f32 v143, v143, v145, v57
	v_max3_f32 v145, v74, v58, v75
	v_max3_f32 v143, v143, v145, v59
	v_max3_f32 v145, v76, v60, v77
	v_max3_f32 v143, v143, v145, v61
	v_max3_f32 v145, v78, v62, v79
	v_max3_f32 v143, v143, v145, v63
	v_mov_b32_e32 v145, v143
	s_nop 1
	v_permlane32_swap_b32_e32 v143, v145
	s_cmp_eq_u32 s65, 1
	s_cselect_b64 s[10:11], -1, 0
	s_cmp_lg_u32 s65, 1
	v_max_f32_e32 v143, v143, v145
	s_cbranch_scc0 .LBB0_600
	v_cmp_lt_f32_e32 vcc, s56, v143
	s_mov_b64 s[36:37], 0
	s_mov_b64 s[28:29], 0
	s_cbranch_vccz .LBB0_596
	v_max_f32_e32 v145, v143, v143
	v_max_f32_e32 v190, 0, v145
	s_mov_b64 s[28:29], -1

.LBB0_596:
	v_exp_f32_e32 v192, v64
	v_exp_f32_e32 v193, v65
	v_exp_f32_e32 v196, v48
	v_exp_f32_e32 v197, v49
	v_exp_f32_e32 v194, v66
	v_exp_f32_e32 v195, v67
	v_exp_f32_e32 v198, v50
	v_exp_f32_e32 v199, v51
	v_exp_f32_e32 v200, v68
	v_exp_f32_e32 v201, v69
	v_pk_add_f32 v[48:49], v[196:197], v[192:193]
	v_exp_f32_e32 v202, v52
	v_exp_f32_e32 v203, v53
	v_pk_add_f32 v[48:49], v[194:195], v[48:49]
	v_exp_f32_e32 v204, v70
	v_exp_f32_e32 v205, v71
	v_pk_add_f32 v[48:49], v[198:199], v[48:49]
	v_exp_f32_e32 v206, v54
	v_exp_f32_e32 v207, v55
	v_pk_add_f32 v[48:49], v[200:201], v[48:49]
	v_exp_f32_e32 v208, v72
	v_exp_f32_e32 v209, v73
	v_pk_add_f32 v[48:49], v[202:203], v[48:49]
	v_exp_f32_e32 v210, v56
	v_exp_f32_e32 v211, v57
	v_pk_add_f32 v[48:49], v[204:205], v[48:49]
	v_exp_f32_e32 v212, v74
	v_exp_f32_e32 v213, v75
	v_pk_add_f32 v[48:49], v[206:207], v[48:49]
	v_exp_f32_e32 v214, v58
	v_exp_f32_e32 v215, v59
	v_pk_add_f32 v[48:49], v[208:209], v[48:49]
	v_exp_f32_e32 v216, v76
	v_exp_f32_e32 v217, v77
	v_pk_add_f32 v[48:49], v[210:211], v[48:49]
	v_exp_f32_e32 v218, v60
	v_exp_f32_e32 v219, v61
	v_pk_add_f32 v[48:49], v[212:213], v[48:49]
	v_exp_f32_e32 v220, v78
	v_exp_f32_e32 v221, v79
	v_pk_add_f32 v[48:49], v[214:215], v[48:49]
	v_exp_f32_e32 v222, v62
	v_exp_f32_e32 v223, v63
	v_pk_add_f32 v[48:49], v[216:217], v[48:49]
	s_mul_i32 s10, s67, 0x2200
	v_pk_add_f32 v[48:49], v[218:219], v[48:49]
	v_add_u32_e32 v56, s10, v133
	v_pk_add_f32 v[48:49], v[220:221], v[48:49]
	v_add_u32_e32 v72, 0x6000, v56
	v_pk_add_f32 v[48:49], v[222:223], v[48:49]
	v_add_u32_e32 v76, 0x7000, v56
	v_pk_add_f32 v[48:49], v[48:49], v[48:49] op_sel:[0,1] op_sel_hi:[1,0]
	v_cvt_pk_bf16_f32 v192, v192, v193
	v_mov_b32_e32 v49, v48
	s_nop 1
	v_permlane32_swap_b32_e32 v48, v49
	v_add_f32_e32 v143, v48, v49
	ds_read2_b64 v[48:51], v72 offset1:2
	ds_read2_b64 v[52:55], v72 offset0:4 offset1:6
	ds_read2_b64 v[56:59], v76 offset0:32 offset1:34
	ds_read2_b64 v[60:63], v76 offset0:36 offset1:38
	ds_read2_b64 v[64:67], v72 offset0:8 offset1:10
	ds_read2_b64 v[68:71], v76 offset0:40 offset1:42
	ds_read2_b64 v[72:75], v72 offset0:12 offset1:14
	ds_read2_b64 v[76:79], v76 offset0:44 offset1:46
	v_cvt_pk_bf16_f32 v193, v194, v195
	v_cvt_pk_bf16_f32 v194, v200, v201
	v_cvt_pk_bf16_f32 v195, v204, v205
	v_cvt_pk_bf16_f32 v196, v196, v197
	v_cvt_pk_bf16_f32 v197, v198, v199
	v_cvt_pk_bf16_f32 v198, v202, v203
	v_cvt_pk_bf16_f32 v199, v206, v207
	v_cvt_pk_bf16_f32 v200, v208, v209
	v_cvt_pk_bf16_f32 v201, v212, v213
	v_cvt_pk_bf16_f32 v202, v216, v217
	v_cvt_pk_bf16_f32 v203, v220, v221
	v_cvt_pk_bf16_f32 v204, v210, v211
	v_cvt_pk_bf16_f32 v205, v214, v215
	v_cvt_pk_bf16_f32 v206, v218, v219
	v_cvt_pk_bf16_f32 v207, v222, v223
	s_setprio 1
	s_waitcnt lgkmcnt(7)
	v_mfma_f32_32x32x16_bf16 v[0:15], v[192:195], v[48:51], v[0:15]
	v_add_f32_e32 v139, v139, v143
	s_waitcnt lgkmcnt(5)
	v_mfma_f32_32x32x16_bf16 v[16:31], v[192:195], v[56:59], v[16:31]
	v_mfma_f32_32x32x16_bf16 v[0:15], v[200:203], v[52:55], v[0:15]
	s_waitcnt lgkmcnt(4)
	v_mfma_f32_32x32x16_bf16 v[16:31], v[200:203], v[60:63], v[16:31]
	s_waitcnt lgkmcnt(3)
	v_mfma_f32_32x32x16_bf16 v[0:15], v[196:199], v[64:67], v[0:15]
	s_waitcnt lgkmcnt(2)
	v_mfma_f32_32x32x16_bf16 v[16:31], v[196:199], v[68:71], v[16:31]
	s_waitcnt lgkmcnt(1)
	v_mfma_f32_32x32x16_bf16 v[0:15], v[204:207], v[72:75], v[0:15]
	s_waitcnt lgkmcnt(0)
	v_mfma_f32_32x32x16_bf16 v[16:31], v[204:207], v[76:79], v[16:31]
	s_setprio 0

.LBB0_619:
	s_nop 8
	v_max3_f32 v145, v49, v65, v64
	v_max_f32_e32 v145, v145, v48
	v_max3_f32 v147, v66, v50, v67
	v_max3_f32 v145, v145, v147, v51
	v_max3_f32 v147, v68, v52, v69
	v_max3_f32 v145, v145, v147, v53
	v_max3_f32 v147, v70, v54, v71
	v_max3_f32 v145, v145, v147, v55
	v_max3_f32 v147, v72, v56, v73
	v_max3_f32 v145, v145, v147, v57
	v_max3_f32 v147, v74, v58, v75
	v_max3_f32 v145, v145, v147, v59
	v_max3_f32 v147, v76, v60, v77
	v_max3_f32 v145, v145, v147, v61
	v_max3_f32 v147, v78, v62, v79
	v_max3_f32 v145, v145, v147, v63
	v_mov_b32_e32 v147, v145
	s_nop 1
	v_permlane32_swap_b32_e32 v145, v147
	s_cmp_eq_u32 s63, 1
	s_cselect_b64 s[10:11], -1, 0
	s_cmp_lg_u32 s63, 1
	v_max_f32_e32 v145, v145, v147
	s_cbranch_scc0 .LBB0_632
	v_cmp_lt_f32_e32 vcc, s56, v145
	s_mov_b64 s[36:37], 0
	s_mov_b64 s[28:29], 0
	s_cbranch_vccz .LBB0_628
	v_max_f32_e32 v147, v145, v145
	v_max_f32_e32 v176, 0, v147
	s_mov_b64 s[28:29], -1

.LBB0_628:
	s_mul_i32 s10, s65, 0x2200
	v_add_u32_e32 v232, s10, v133
	v_add_u32_e32 v233, 0x7000, v232
	v_add_u32_e32 v232, 0x6000, v232
	ds_read2_b64 v[212:215], v232 offset1:2
	ds_read2_b64 v[216:219], v232 offset0:4 offset1:6
	ds_read2_b64 v[220:223], v233 offset0:32 offset1:34
	ds_read2_b64 v[224:227], v233 offset0:36 offset1:38
	ds_read2_b64 v[228:231], v232 offset0:8 offset1:10
	v_exp_f32_e32 v176, v64
	v_exp_f32_e32 v177, v65
	v_exp_f32_e32 v180, v48
	v_exp_f32_e32 v181, v49
	v_exp_f32_e32 v178, v66
	v_exp_f32_e32 v179, v67
	v_exp_f32_e32 v186, v50
	v_exp_f32_e32 v187, v51
	v_exp_f32_e32 v184, v68
	v_exp_f32_e32 v185, v69
	v_pk_add_f32 v[48:49], v[180:181], v[176:177]
	v_exp_f32_e32 v188, v52
	v_exp_f32_e32 v189, v53
	v_pk_add_f32 v[48:49], v[178:179], v[48:49]
	v_exp_f32_e32 v192, v70
	v_exp_f32_e32 v193, v71
	v_pk_add_f32 v[48:49], v[186:187], v[48:49]
	v_exp_f32_e32 v194, v54
	v_exp_f32_e32 v195, v55
	v_pk_add_f32 v[48:49], v[184:185], v[48:49]
	v_exp_f32_e32 v196, v72
	v_exp_f32_e32 v197, v73
	v_pk_add_f32 v[48:49], v[188:189], v[48:49]
	v_exp_f32_e32 v198, v56
	v_exp_f32_e32 v199, v57
	v_pk_add_f32 v[48:49], v[192:193], v[48:49]
	v_exp_f32_e32 v200, v74
	v_exp_f32_e32 v201, v75
	v_pk_add_f32 v[48:49], v[194:195], v[48:49]
	v_exp_f32_e32 v202, v58
	v_exp_f32_e32 v203, v59
	v_pk_add_f32 v[48:49], v[196:197], v[48:49]
	v_exp_f32_e32 v204, v76
	v_exp_f32_e32 v205, v77
	v_pk_add_f32 v[48:49], v[198:199], v[48:49]
	v_exp_f32_e32 v206, v60
	v_exp_f32_e32 v207, v61
	v_pk_add_f32 v[48:49], v[200:201], v[48:49]
	v_exp_f32_e32 v208, v78
	v_exp_f32_e32 v209, v79
	v_pk_add_f32 v[48:49], v[202:203], v[48:49]
	v_exp_f32_e32 v210, v62
	v_exp_f32_e32 v211, v63
	v_pk_add_f32 v[48:49], v[204:205], v[48:49]
	s_mul_i32 s10, s65, 0x2200
	v_pk_add_f32 v[48:49], v[206:207], v[48:49]
	v_add_u32_e32 v56, s10, v133
	v_pk_add_f32 v[48:49], v[208:209], v[48:49]
	v_add_u32_e32 v72, 0x6000, v56
	v_pk_add_f32 v[48:49], v[210:211], v[48:49]
	v_add_u32_e32 v76, 0x7000, v56
	v_pk_add_f32 v[48:49], v[48:49], v[48:49] op_sel:[0,1] op_sel_hi:[1,0]
	v_cvt_pk_bf16_f32 v176, v176, v177
	v_mov_b32_e32 v49, v48
	s_nop 1
	v_permlane32_swap_b32_e32 v48, v49
	v_add_f32_e32 v145, v48, v49
	ds_read2_b64 v[68:71], v76 offset0:40 offset1:42
	ds_read2_b64 v[72:75], v72 offset0:12 offset1:14
	ds_read2_b64 v[76:79], v76 offset0:44 offset1:46
	v_cvt_pk_bf16_f32 v177, v178, v179
	v_cvt_pk_bf16_f32 v178, v184, v185
	v_cvt_pk_bf16_f32 v179, v192, v193
	v_cvt_pk_bf16_f32 v184, v180, v181
	v_cvt_pk_bf16_f32 v185, v186, v187
	v_cvt_pk_bf16_f32 v186, v188, v189
	v_cvt_pk_bf16_f32 v187, v194, v195
	v_cvt_pk_bf16_f32 v192, v196, v197
	v_cvt_pk_bf16_f32 v193, v200, v201
	v_cvt_pk_bf16_f32 v194, v204, v205
	v_cvt_pk_bf16_f32 v195, v208, v209
	v_cvt_pk_bf16_f32 v196, v198, v199
	v_cvt_pk_bf16_f32 v197, v202, v203
	v_cvt_pk_bf16_f32 v198, v206, v207
	v_cvt_pk_bf16_f32 v199, v210, v211
	s_setprio 1
	s_waitcnt lgkmcnt(7)
	v_mfma_f32_32x32x16_bf16 v[0:15], v[176:179], v[212:215], v[0:15]
	v_add_f32_e32 v141, v141, v145
	s_waitcnt lgkmcnt(5)
	v_mfma_f32_32x32x16_bf16 v[16:31], v[176:179], v[220:223], v[16:31]
	v_mfma_f32_32x32x16_bf16 v[0:15], v[192:195], v[216:219], v[0:15]
	s_waitcnt lgkmcnt(4)
	v_mfma_f32_32x32x16_bf16 v[16:31], v[192:195], v[224:227], v[16:31]
	s_waitcnt lgkmcnt(3)
	v_mfma_f32_32x32x16_bf16 v[0:15], v[184:187], v[228:231], v[0:15]
	s_waitcnt lgkmcnt(2)
	v_mfma_f32_32x32x16_bf16 v[16:31], v[184:187], v[68:71], v[16:31]
	s_waitcnt lgkmcnt(1)
	v_mfma_f32_32x32x16_bf16 v[0:15], v[196:199], v[72:75], v[0:15]
	s_waitcnt lgkmcnt(0)
	v_mfma_f32_32x32x16_bf16 v[16:31], v[196:199], v[76:79], v[16:31]
	s_setprio 0

.LBB0_822:
	v_and_b32_e32 v144, 15, v191
	v_lshrrev_b32_e32 v145, 2, v191
	v_and_or_b32 v144, v145, 64, v144
	v_lshrrev_b32_e32 v145, 1, v191
	v_and_b32_e32 v145, 0x78, v145
	v_lshlrev_b32_e32 v145, 1, v145
	v_mul_u32_u24_e32 v146, 0x1a00, v144
	v_add_u32_e32 v146, v146, v145
	v_lshl_add_u32 v147, v144, 11, v145
	s_mul_i32 s28, s52, 0x1a0000
	s_lshl_b32 s29, s53, 9
	s_add_i32 s28, s28, s29
	s_addk_i32 s28, 0x800
	s_add_u32 s98, s14, s28
	s_addc_u32 s99, s15, 0
	s_lshl_b32 s28, s52, 19
	s_add_i32 s28, s28, s29
	s_add_u32 s100, s8, s28
	s_addc_u32 s101, s9, 0
	s_add_u32 s10, s20, s28
	s_addc_u32 s11, s21, 0
	v_mov_b32_e32 v144, v146
	v_mov_b32_e32 v145, v147
	global_load_dwordx4 v[158:161], v144, s[98:99]
	global_load_dwordx4 v[192:195], v145, s[100:101]
	v_add_u32_e32 v144, 0x1a000, v146
	v_add_u32_e32 v145, 0x8000, v147
	global_load_dwordx4 v[162:165], v144, s[98:99]
	global_load_dwordx4 v[196:199], v145, s[100:101]
	v_add_u32_e32 v144, 0x34000, v146
	v_add_u32_e32 v145, 0x10000, v147
	global_load_dwordx4 v[166:169], v144, s[98:99]
	global_load_dwordx4 v[200:203], v145, s[100:101]
	v_add_u32_e32 v144, 0x4e000, v146
	v_add_u32_e32 v145, 0x18000, v147
	global_load_dwordx4 v[170:173], v144, s[98:99]
	global_load_dwordx4 v[204:207], v145, s[100:101]
	v_add_u32_e32 v144, 0xd0000, v146
	v_add_u32_e32 v145, 0x40000, v147
	global_load_dwordx4 v[174:177], v144, s[98:99]
	global_load_dwordx4 v[208:211], v145, s[100:101]
	v_add_u32_e32 v144, 0xea000, v146
	v_add_u32_e32 v145, 0x48000, v147
	global_load_dwordx4 v[178:181], v144, s[98:99]
	global_load_dwordx4 v[212:215], v145, s[100:101]
	s_waitcnt vmcnt(10)
	v_lshlrev_b32_e32 v182, 16, v158
	v_and_b32_e32 v183, 0xffff0000, v158
	v_lshlrev_b32_e32 v216, 16, v192
	v_and_b32_e32 v217, 0xffff0000, v192
	v_lshlrev_b32_e32 v184, 16, v159
	v_and_b32_e32 v185, 0xffff0000, v159
	v_lshlrev_b32_e32 v218, 16, v193
	v_and_b32_e32 v219, 0xffff0000, v193
	v_lshlrev_b32_e32 v186, 16, v160
	v_and_b32_e32 v187, 0xffff0000, v160
	v_lshlrev_b32_e32 v220, 16, v194
	v_and_b32_e32 v221, 0xffff0000, v194
	v_lshlrev_b32_e32 v188, 16, v161
	v_and_b32_e32 v189, 0xffff0000, v161
	v_lshlrev_b32_e32 v222, 16, v195
	v_and_b32_e32 v223, 0xffff0000, v195
	v_pk_fma_f32 v[124:125], v[124:125], v[182:183], v[216:217]
	v_pk_fma_f32 v[126:127], v[126:127], v[184:185], v[218:219]
	v_pk_fma_f32 v[120:121], v[120:121], v[186:187], v[220:221]
	v_pk_fma_f32 v[122:123], v[122:123], v[188:189], v[222:223]
	v_cvt_pk_bf16_f32 v150, v124, v125
	v_cvt_pk_bf16_f32 v151, v126, v127
	v_cvt_pk_bf16_f32 v152, v120, v121
	v_cvt_pk_bf16_f32 v153, v122, v123
	v_mov_b32_e32 v149, v147
	global_store_dwordx4 v149, v[150:153], s[10:11]
	v_add_u32_e32 v144, 0x104000, v146
	v_add_u32_e32 v145, 0x50000, v147
	global_load_dwordx4 v[158:161], v144, s[98:99]
	global_load_dwordx4 v[192:195], v145, s[100:101]
	s_waitcnt vmcnt(11)
	v_lshlrev_b32_e32 v182, 16, v162
	v_and_b32_e32 v183, 0xffff0000, v162
	v_lshlrev_b32_e32 v216, 16, v196
	v_and_b32_e32 v217, 0xffff0000, v196
	v_lshlrev_b32_e32 v184, 16, v163
	v_and_b32_e32 v185, 0xffff0000, v163
	v_lshlrev_b32_e32 v218, 16, v197
	v_and_b32_e32 v219, 0xffff0000, v197
	v_lshlrev_b32_e32 v186, 16, v164
	v_and_b32_e32 v187, 0xffff0000, v164
	v_lshlrev_b32_e32 v220, 16, v198
	v_and_b32_e32 v221, 0xffff0000, v198
	v_lshlrev_b32_e32 v188, 16, v165
	v_and_b32_e32 v189, 0xffff0000, v165
	v_lshlrev_b32_e32 v222, 16, v199
	v_and_b32_e32 v223, 0xffff0000, v199
	v_pk_fma_f32 v[116:117], v[116:117], v[182:183], v[216:217]
	v_pk_fma_f32 v[118:119], v[118:119], v[184:185], v[218:219]
	v_pk_fma_f32 v[112:113], v[112:113], v[186:187], v[220:221]
	v_pk_fma_f32 v[114:115], v[114:115], v[188:189], v[222:223]
	v_cvt_pk_bf16_f32 v150, v116, v117
	v_cvt_pk_bf16_f32 v151, v118, v119
	v_cvt_pk_bf16_f32 v152, v112, v113
	v_cvt_pk_bf16_f32 v153, v114, v115
	v_add_u32_e32 v149, 0x8000, v147
	global_store_dwordx4 v149, v[150:153], s[10:11]
	v_add_u32_e32 v144, 0x11e000, v146
	v_add_u32_e32 v145, 0x58000, v147
	global_load_dwordx4 v[162:165], v144, s[98:99]
	global_load_dwordx4 v[196:199], v145, s[100:101]
	s_waitcnt vmcnt(12)
	v_lshlrev_b32_e32 v182, 16, v166
	v_and_b32_e32 v183, 0xffff0000, v166
	v_lshlrev_b32_e32 v216, 16, v200
	v_and_b32_e32 v217, 0xffff0000, v200
	v_lshlrev_b32_e32 v184, 16, v167
	v_and_b32_e32 v185, 0xffff0000, v167
	v_lshlrev_b32_e32 v218, 16, v201
	v_and_b32_e32 v219, 0xffff0000, v201
	v_lshlrev_b32_e32 v186, 16, v168
	v_and_b32_e32 v187, 0xffff0000, v168
	v_lshlrev_b32_e32 v220, 16, v202
	v_and_b32_e32 v221, 0xffff0000, v202
	v_lshlrev_b32_e32 v188, 16, v169
	v_and_b32_e32 v189, 0xffff0000, v169
	v_lshlrev_b32_e32 v222, 16, v203
	v_and_b32_e32 v223, 0xffff0000, v203
	v_pk_fma_f32 v[108:109], v[108:109], v[182:183], v[216:217]
	v_pk_fma_f32 v[110:111], v[110:111], v[184:185], v[218:219]
	v_pk_fma_f32 v[104:105], v[104:105], v[186:187], v[220:221]
	v_pk_fma_f32 v[106:107], v[106:107], v[188:189], v[222:223]
	v_cvt_pk_bf16_f32 v150, v108, v109
	v_cvt_pk_bf16_f32 v151, v110, v111
	v_cvt_pk_bf16_f32 v152, v104, v105
	v_cvt_pk_bf16_f32 v153, v106, v107
	v_add_u32_e32 v149, 0x10000, v147
	global_store_dwordx4 v149, v[150:153], s[10:11]
	v_add_u32_e32 v144, 0x100, v146
	v_add_u32_e32 v145, 0x100, v147
	global_load_dwordx4 v[166:169], v144, s[98:99]
	global_load_dwordx4 v[200:203], v145, s[100:101]
	s_waitcnt vmcnt(13)
	v_lshlrev_b32_e32 v182, 16, v170
	v_and_b32_e32 v183, 0xffff0000, v170
	v_lshlrev_b32_e32 v216, 16, v204
	v_and_b32_e32 v217, 0xffff0000, v204
	v_lshlrev_b32_e32 v184, 16, v171
	v_and_b32_e32 v185, 0xffff0000, v171
	v_lshlrev_b32_e32 v218, 16, v205
	v_and_b32_e32 v219, 0xffff0000, v205
	v_lshlrev_b32_e32 v186, 16, v172
	v_and_b32_e32 v187, 0xffff0000, v172
	v_lshlrev_b32_e32 v220, 16, v206
	v_and_b32_e32 v221, 0xffff0000, v206
	v_lshlrev_b32_e32 v188, 16, v173
	v_and_b32_e32 v189, 0xffff0000, v173
	v_lshlrev_b32_e32 v222, 16, v207
	v_and_b32_e32 v223, 0xffff0000, v207
	v_pk_fma_f32 v[100:101], v[100:101], v[182:183], v[216:217]
	v_pk_fma_f32 v[102:103], v[102:103], v[184:185], v[218:219]
	v_pk_fma_f32 v[96:97], v[96:97], v[186:187], v[220:221]
	v_pk_fma_f32 v[98:99], v[98:99], v[188:189], v[222:223]
	v_cvt_pk_bf16_f32 v150, v100, v101
	v_cvt_pk_bf16_f32 v151, v102, v103
	v_cvt_pk_bf16_f32 v152, v96, v97
	v_cvt_pk_bf16_f32 v153, v98, v99
	v_add_u32_e32 v149, 0x18000, v147
	global_store_dwordx4 v149, v[150:153], s[10:11]
	v_add_u32_e32 v144, 0x1a100, v146
	v_add_u32_e32 v145, 0x8100, v147
	global_load_dwordx4 v[170:173], v144, s[98:99]
	global_load_dwordx4 v[204:207], v145, s[100:101]
	s_waitcnt vmcnt(14)
	v_lshlrev_b32_e32 v182, 16, v174
	v_and_b32_e32 v183, 0xffff0000, v174
	v_lshlrev_b32_e32 v216, 16, v208
	v_and_b32_e32 v217, 0xffff0000, v208
	v_lshlrev_b32_e32 v184, 16, v175
	v_and_b32_e32 v185, 0xffff0000, v175
	v_lshlrev_b32_e32 v218, 16, v209
	v_and_b32_e32 v219, 0xffff0000, v209
	v_lshlrev_b32_e32 v186, 16, v176
	v_and_b32_e32 v187, 0xffff0000, v176
	v_lshlrev_b32_e32 v220, 16, v210
	v_and_b32_e32 v221, 0xffff0000, v210
	v_lshlrev_b32_e32 v188, 16, v177
	v_and_b32_e32 v189, 0xffff0000, v177
	v_lshlrev_b32_e32 v222, 16, v211
	v_and_b32_e32 v223, 0xffff0000, v211
	v_pk_fma_f32 v[92:93], v[92:93], v[182:183], v[216:217]
	v_pk_fma_f32 v[94:95], v[94:95], v[184:185], v[218:219]
	v_pk_fma_f32 v[88:89], v[88:89], v[186:187], v[220:221]
	v_pk_fma_f32 v[90:91], v[90:91], v[188:189], v[222:223]
	v_cvt_pk_bf16_f32 v150, v92, v93
	v_cvt_pk_bf16_f32 v151, v94, v95
	v_cvt_pk_bf16_f32 v152, v88, v89
	v_cvt_pk_bf16_f32 v153, v90, v91
	v_add_u32_e32 v149, 0x40000, v147
	global_store_dwordx4 v149, v[150:153], s[10:11]
	v_add_u32_e32 v144, 0x34100, v146
	v_add_u32_e32 v145, 0x10100, v147
	global_load_dwordx4 v[174:177], v144, s[98:99]
	global_load_dwordx4 v[208:211], v145, s[100:101]
	s_waitcnt vmcnt(15)
	v_lshlrev_b32_e32 v182, 16, v178
	v_and_b32_e32 v183, 0xffff0000, v178
	v_lshlrev_b32_e32 v216, 16, v212
	v_and_b32_e32 v217, 0xffff0000, v212
	v_lshlrev_b32_e32 v184, 16, v179
	v_and_b32_e32 v185, 0xffff0000, v179
	v_lshlrev_b32_e32 v218, 16, v213
	v_and_b32_e32 v219, 0xffff0000, v213
	v_lshlrev_b32_e32 v186, 16, v180
	v_and_b32_e32 v187, 0xffff0000, v180
	v_lshlrev_b32_e32 v220, 16, v214
	v_and_b32_e32 v221, 0xffff0000, v214
	v_lshlrev_b32_e32 v188, 16, v181
	v_and_b32_e32 v189, 0xffff0000, v181
	v_lshlrev_b32_e32 v222, 16, v215
	v_and_b32_e32 v223, 0xffff0000, v215
	v_pk_fma_f32 v[84:85], v[84:85], v[182:183], v[216:217]
	v_pk_fma_f32 v[86:87], v[86:87], v[184:185], v[218:219]
	v_pk_fma_f32 v[80:81], v[80:81], v[186:187], v[220:221]
	v_pk_fma_f32 v[82:83], v[82:83], v[188:189], v[222:223]
	v_cvt_pk_bf16_f32 v150, v84, v85
	v_cvt_pk_bf16_f32 v151, v86, v87
	v_cvt_pk_bf16_f32 v152, v80, v81
	v_cvt_pk_bf16_f32 v153, v82, v83
	v_add_u32_e32 v149, 0x48000, v147
	global_store_dwordx4 v149, v[150:153], s[10:11]
	v_add_u32_e32 v144, 0x4e100, v146
	v_add_u32_e32 v145, 0x18100, v147
	global_load_dwordx4 v[178:181], v144, s[98:99]
	global_load_dwordx4 v[212:215], v145, s[100:101]
	s_waitcnt vmcnt(15)
	v_lshlrev_b32_e32 v182, 16, v158
	v_and_b32_e32 v183, 0xffff0000, v158
	v_lshlrev_b32_e32 v216, 16, v192
	v_and_b32_e32 v217, 0xffff0000, v192
	v_lshlrev_b32_e32 v184, 16, v159
	v_and_b32_e32 v185, 0xffff0000, v159
	v_lshlrev_b32_e32 v218, 16, v193
	v_and_b32_e32 v219, 0xffff0000, v193
	v_lshlrev_b32_e32 v186, 16, v160
	v_and_b32_e32 v187, 0xffff0000, v160
	v_lshlrev_b32_e32 v220, 16, v194
	v_and_b32_e32 v221, 0xffff0000, v194
	v_lshlrev_b32_e32 v188, 16, v161
	v_and_b32_e32 v189, 0xffff0000, v161
	v_lshlrev_b32_e32 v222, 16, v195
	v_and_b32_e32 v223, 0xffff0000, v195
	v_pk_fma_f32 v[76:77], v[76:77], v[182:183], v[216:217]
	v_pk_fma_f32 v[78:79], v[78:79], v[184:185], v[218:219]
	v_pk_fma_f32 v[72:73], v[72:73], v[186:187], v[220:221]
	v_pk_fma_f32 v[74:75], v[74:75], v[188:189], v[222:223]
	v_cvt_pk_bf16_f32 v150, v76, v77
	v_cvt_pk_bf16_f32 v151, v78, v79
	v_cvt_pk_bf16_f32 v152, v72, v73
	v_cvt_pk_bf16_f32 v153, v74, v75
	v_add_u32_e32 v149, 0x50000, v147
	global_store_dwordx4 v149, v[150:153], s[10:11]
	v_add_u32_e32 v144, 0xd0100, v146
	v_add_u32_e32 v145, 0x40100, v147
	global_load_dwordx4 v[158:161], v144, s[98:99]
	global_load_dwordx4 v[192:195], v145, s[100:101]
	s_waitcnt vmcnt(15)
	v_lshlrev_b32_e32 v182, 16, v162
	v_and_b32_e32 v183, 0xffff0000, v162
	v_lshlrev_b32_e32 v216, 16, v196
	v_and_b32_e32 v217, 0xffff0000, v196
	v_lshlrev_b32_e32 v184, 16, v163
	v_and_b32_e32 v185, 0xffff0000, v163
	v_lshlrev_b32_e32 v218, 16, v197
	v_and_b32_e32 v219, 0xffff0000, v197
	v_lshlrev_b32_e32 v186, 16, v164
	v_and_b32_e32 v187, 0xffff0000, v164
	v_lshlrev_b32_e32 v220, 16, v198
	v_and_b32_e32 v221, 0xffff0000, v198
	v_lshlrev_b32_e32 v188, 16, v165
	v_and_b32_e32 v189, 0xffff0000, v165
	v_lshlrev_b32_e32 v222, 16, v199
	v_and_b32_e32 v223, 0xffff0000, v199
	v_pk_fma_f32 v[68:69], v[68:69], v[182:183], v[216:217]
	v_pk_fma_f32 v[70:71], v[70:71], v[184:185], v[218:219]
	v_pk_fma_f32 v[64:65], v[64:65], v[186:187], v[220:221]
	v_pk_fma_f32 v[66:67], v[66:67], v[188:189], v[222:223]
	v_cvt_pk_bf16_f32 v150, v68, v69
	v_cvt_pk_bf16_f32 v151, v70, v71
	v_cvt_pk_bf16_f32 v152, v64, v65
	v_cvt_pk_bf16_f32 v153, v66, v67
	v_add_u32_e32 v149, 0x58000, v147
	global_store_dwordx4 v149, v[150:153], s[10:11]
	v_add_u32_e32 v144, 0xea100, v146
	v_add_u32_e32 v145, 0x48100, v147
	global_load_dwordx4 v[162:165], v144, s[98:99]
	global_load_dwordx4 v[196:199], v145, s[100:101]
	s_waitcnt vmcnt(15)
	v_lshlrev_b32_e32 v182, 16, v166
	v_and_b32_e32 v183, 0xffff0000, v166
	v_lshlrev_b32_e32 v216, 16, v200
	v_and_b32_e32 v217, 0xffff0000, v200
	v_lshlrev_b32_e32 v184, 16, v167
	v_and_b32_e32 v185, 0xffff0000, v167
	v_lshlrev_b32_e32 v218, 16, v201
	v_and_b32_e32 v219, 0xffff0000, v201
	v_lshlrev_b32_e32 v186, 16, v168
	v_and_b32_e32 v187, 0xffff0000, v168
	v_lshlrev_b32_e32 v220, 16, v202
	v_and_b32_e32 v221, 0xffff0000, v202
	v_lshlrev_b32_e32 v188, 16, v169
	v_and_b32_e32 v189, 0xffff0000, v169
	v_lshlrev_b32_e32 v222, 16, v203
	v_and_b32_e32 v223, 0xffff0000, v203
	v_pk_fma_f32 v[60:61], v[60:61], v[182:183], v[216:217]
	v_pk_fma_f32 v[62:63], v[62:63], v[184:185], v[218:219]
	v_pk_fma_f32 v[56:57], v[56:57], v[186:187], v[220:221]
	v_pk_fma_f32 v[58:59], v[58:59], v[188:189], v[222:223]
	v_cvt_pk_bf16_f32 v150, v60, v61
	v_cvt_pk_bf16_f32 v151, v62, v63
	v_cvt_pk_bf16_f32 v152, v56, v57
	v_cvt_pk_bf16_f32 v153, v58, v59
	v_add_u32_e32 v149, 0x100, v147
	global_store_dwordx4 v149, v[150:153], s[10:11]
	v_add_u32_e32 v144, 0x104100, v146
	v_add_u32_e32 v145, 0x50100, v147
	global_load_dwordx4 v[166:169], v144, s[98:99]
	global_load_dwordx4 v[200:203], v145, s[100:101]
	s_waitcnt vmcnt(15)
	v_lshlrev_b32_e32 v182, 16, v170
	v_and_b32_e32 v183, 0xffff0000, v170
	v_lshlrev_b32_e32 v216, 16, v204
	v_and_b32_e32 v217, 0xffff0000, v204
	v_lshlrev_b32_e32 v184, 16, v171
	v_and_b32_e32 v185, 0xffff0000, v171
	v_lshlrev_b32_e32 v218, 16, v205
	v_and_b32_e32 v219, 0xffff0000, v205
	v_lshlrev_b32_e32 v186, 16, v172
	v_and_b32_e32 v187, 0xffff0000, v172
	v_lshlrev_b32_e32 v220, 16, v206
	v_and_b32_e32 v221, 0xffff0000, v206
	v_lshlrev_b32_e32 v188, 16, v173
	v_and_b32_e32 v189, 0xffff0000, v173
	v_lshlrev_b32_e32 v222, 16, v207
	v_and_b32_e32 v223, 0xffff0000, v207
	v_pk_fma_f32 v[52:53], v[52:53], v[182:183], v[216:217]
	v_pk_fma_f32 v[54:55], v[54:55], v[184:185], v[218:219]
	v_pk_fma_f32 v[48:49], v[48:49], v[186:187], v[220:221]
	v_pk_fma_f32 v[50:51], v[50:51], v[188:189], v[222:223]
	v_cvt_pk_bf16_f32 v150, v52, v53
	v_cvt_pk_bf16_f32 v151, v54, v55
	v_cvt_pk_bf16_f32 v152, v48, v49
	v_cvt_pk_bf16_f32 v153, v50, v51
	v_add_u32_e32 v149, 0x8100, v147
	global_store_dwordx4 v149, v[150:153], s[10:11]
	v_add_u32_e32 v144, 0x11e100, v146
	v_add_u32_e32 v145, 0x58100, v147
	global_load_dwordx4 v[170:173], v144, s[98:99]
	global_load_dwordx4 v[204:207], v145, s[100:101]
	s_waitcnt vmcnt(15)
	v_lshlrev_b32_e32 v182, 16, v174
	v_and_b32_e32 v183, 0xffff0000, v174
	v_lshlrev_b32_e32 v216, 16, v208
	v_and_b32_e32 v217, 0xffff0000, v208
	v_lshlrev_b32_e32 v184, 16, v175
	v_and_b32_e32 v185, 0xffff0000, v175
	v_lshlrev_b32_e32 v218, 16, v209
	v_and_b32_e32 v219, 0xffff0000, v209
	v_lshlrev_b32_e32 v186, 16, v176
	v_and_b32_e32 v187, 0xffff0000, v176
	v_lshlrev_b32_e32 v220, 16, v210
	v_and_b32_e32 v221, 0xffff0000, v210
	v_lshlrev_b32_e32 v188, 16, v177
	v_and_b32_e32 v189, 0xffff0000, v177
	v_lshlrev_b32_e32 v222, 16, v211
	v_and_b32_e32 v223, 0xffff0000, v211
	v_pk_fma_f32 v[44:45], v[44:45], v[182:183], v[216:217]
	v_pk_fma_f32 v[46:47], v[46:47], v[184:185], v[218:219]
	v_pk_fma_f32 v[40:41], v[40:41], v[186:187], v[220:221]
	v_pk_fma_f32 v[42:43], v[42:43], v[188:189], v[222:223]
	v_cvt_pk_bf16_f32 v150, v44, v45
	v_cvt_pk_bf16_f32 v151, v46, v47
	v_cvt_pk_bf16_f32 v152, v40, v41
	v_cvt_pk_bf16_f32 v153, v42, v43
	v_add_u32_e32 v149, 0x10100, v147
	global_store_dwordx4 v149, v[150:153], s[10:11]
	s_waitcnt vmcnt(13)
	v_lshlrev_b32_e32 v182, 16, v178
	v_and_b32_e32 v183, 0xffff0000, v178
	v_lshlrev_b32_e32 v216, 16, v212
	v_and_b32_e32 v217, 0xffff0000, v212
	v_lshlrev_b32_e32 v184, 16, v179
	v_and_b32_e32 v185, 0xffff0000, v179
	v_lshlrev_b32_e32 v218, 16, v213
	v_and_b32_e32 v219, 0xffff0000, v213
	v_lshlrev_b32_e32 v186, 16, v180
	v_and_b32_e32 v187, 0xffff0000, v180
	v_lshlrev_b32_e32 v220, 16, v214
	v_and_b32_e32 v221, 0xffff0000, v214
	v_lshlrev_b32_e32 v188, 16, v181
	v_and_b32_e32 v189, 0xffff0000, v181
	v_lshlrev_b32_e32 v222, 16, v215
	v_and_b32_e32 v223, 0xffff0000, v215
	v_pk_fma_f32 v[36:37], v[36:37], v[182:183], v[216:217]
	v_pk_fma_f32 v[38:39], v[38:39], v[184:185], v[218:219]
	v_pk_fma_f32 v[32:33], v[32:33], v[186:187], v[220:221]
	v_pk_fma_f32 v[34:35], v[34:35], v[188:189], v[222:223]
	v_cvt_pk_bf16_f32 v150, v36, v37
	v_cvt_pk_bf16_f32 v151, v38, v39
	v_cvt_pk_bf16_f32 v152, v32, v33
	v_cvt_pk_bf16_f32 v153, v34, v35
	v_add_u32_e32 v149, 0x18100, v147
	global_store_dwordx4 v149, v[150:153], s[10:11]
	s_waitcnt vmcnt(11)
	v_lshlrev_b32_e32 v182, 16, v158
	v_and_b32_e32 v183, 0xffff0000, v158
	v_lshlrev_b32_e32 v216, 16, v192
	v_and_b32_e32 v217, 0xffff0000, v192
	v_lshlrev_b32_e32 v184, 16, v159
	v_and_b32_e32 v185, 0xffff0000, v159
	v_lshlrev_b32_e32 v218, 16, v193
	v_and_b32_e32 v219, 0xffff0000, v193
	v_lshlrev_b32_e32 v186, 16, v160
	v_and_b32_e32 v187, 0xffff0000, v160
	v_lshlrev_b32_e32 v220, 16, v194
	v_and_b32_e32 v221, 0xffff0000, v194
	v_lshlrev_b32_e32 v188, 16, v161
	v_and_b32_e32 v189, 0xffff0000, v161
	v_lshlrev_b32_e32 v222, 16, v195
	v_and_b32_e32 v223, 0xffff0000, v195
	v_pk_fma_f32 v[28:29], v[28:29], v[182:183], v[216:217]
	v_pk_fma_f32 v[30:31], v[30:31], v[184:185], v[218:219]
	v_pk_fma_f32 v[24:25], v[24:25], v[186:187], v[220:221]
	v_pk_fma_f32 v[26:27], v[26:27], v[188:189], v[222:223]
	v_cvt_pk_bf16_f32 v150, v28, v29
	v_cvt_pk_bf16_f32 v151, v30, v31
	v_cvt_pk_bf16_f32 v152, v24, v25
	v_cvt_pk_bf16_f32 v153, v26, v27
	v_add_u32_e32 v149, 0x40100, v147
	global_store_dwordx4 v149, v[150:153], s[10:11]
	s_waitcnt vmcnt(9)
	v_lshlrev_b32_e32 v182, 16, v162
	v_and_b32_e32 v183, 0xffff0000, v162
	v_lshlrev_b32_e32 v216, 16, v196
	v_and_b32_e32 v217, 0xffff0000, v196
	v_lshlrev_b32_e32 v184, 16, v163
	v_and_b32_e32 v185, 0xffff0000, v163
	v_lshlrev_b32_e32 v218, 16, v197
	v_and_b32_e32 v219, 0xffff0000, v197
	v_lshlrev_b32_e32 v186, 16, v164
	v_and_b32_e32 v187, 0xffff0000, v164
	v_lshlrev_b32_e32 v220, 16, v198
	v_and_b32_e32 v221, 0xffff0000, v198
	v_lshlrev_b32_e32 v188, 16, v165
	v_and_b32_e32 v189, 0xffff0000, v165
	v_lshlrev_b32_e32 v222, 16, v199
	v_and_b32_e32 v223, 0xffff0000, v199
	v_pk_fma_f32 v[20:21], v[20:21], v[182:183], v[216:217]
	v_pk_fma_f32 v[22:23], v[22:23], v[184:185], v[218:219]
	v_pk_fma_f32 v[16:17], v[16:17], v[186:187], v[220:221]
	v_pk_fma_f32 v[18:19], v[18:19], v[188:189], v[222:223]
	v_cvt_pk_bf16_f32 v150, v20, v21
	v_cvt_pk_bf16_f32 v151, v22, v23
	v_cvt_pk_bf16_f32 v152, v16, v17
	v_cvt_pk_bf16_f32 v153, v18, v19
	v_add_u32_e32 v149, 0x48100, v147
	global_store_dwordx4 v149, v[150:153], s[10:11]
	s_waitcnt vmcnt(7)
	v_lshlrev_b32_e32 v182, 16, v166
	v_and_b32_e32 v183, 0xffff0000, v166
	v_lshlrev_b32_e32 v216, 16, v200
	v_and_b32_e32 v217, 0xffff0000, v200
	v_lshlrev_b32_e32 v184, 16, v167
	v_and_b32_e32 v185, 0xffff0000, v167
	v_lshlrev_b32_e32 v218, 16, v201
	v_and_b32_e32 v219, 0xffff0000, v201
	v_lshlrev_b32_e32 v186, 16, v168
	v_and_b32_e32 v187, 0xffff0000, v168
	v_lshlrev_b32_e32 v220, 16, v202
	v_and_b32_e32 v221, 0xffff0000, v202
	v_lshlrev_b32_e32 v188, 16, v169
	v_and_b32_e32 v189, 0xffff0000, v169
	v_lshlrev_b32_e32 v222, 16, v203
	v_and_b32_e32 v223, 0xffff0000, v203
	v_pk_fma_f32 v[12:13], v[12:13], v[182:183], v[216:217]
	v_pk_fma_f32 v[14:15], v[14:15], v[184:185], v[218:219]
	v_pk_fma_f32 v[8:9], v[8:9], v[186:187], v[220:221]
	v_pk_fma_f32 v[10:11], v[10:11], v[188:189], v[222:223]
	v_cvt_pk_bf16_f32 v150, v12, v13
	v_cvt_pk_bf16_f32 v151, v14, v15
	v_cvt_pk_bf16_f32 v152, v8, v9
	v_cvt_pk_bf16_f32 v153, v10, v11
	v_add_u32_e32 v149, 0x50100, v147
	global_store_dwordx4 v149, v[150:153], s[10:11]
	s_waitcnt vmcnt(5)
	v_lshlrev_b32_e32 v182, 16, v170
	v_and_b32_e32 v183, 0xffff0000, v170
	v_lshlrev_b32_e32 v216, 16, v204
	v_and_b32_e32 v217, 0xffff0000, v204
	v_lshlrev_b32_e32 v184, 16, v171
	v_and_b32_e32 v185, 0xffff0000, v171
	v_lshlrev_b32_e32 v218, 16, v205
	v_and_b32_e32 v219, 0xffff0000, v205
	v_lshlrev_b32_e32 v186, 16, v172
	v_and_b32_e32 v187, 0xffff0000, v172
	v_lshlrev_b32_e32 v220, 16, v206
	v_and_b32_e32 v221, 0xffff0000, v206
	v_lshlrev_b32_e32 v188, 16, v173
	v_and_b32_e32 v189, 0xffff0000, v173
	v_lshlrev_b32_e32 v222, 16, v207
	v_and_b32_e32 v223, 0xffff0000, v207
	v_pk_fma_f32 v[4:5], v[4:5], v[182:183], v[216:217]
	v_pk_fma_f32 v[6:7], v[6:7], v[184:185], v[218:219]
	v_pk_fma_f32 v[0:1], v[0:1], v[186:187], v[220:221]
	v_pk_fma_f32 v[2:3], v[2:3], v[188:189], v[222:223]
	v_cvt_pk_bf16_f32 v150, v4, v5
	v_cvt_pk_bf16_f32 v151, v6, v7
	v_cvt_pk_bf16_f32 v152, v0, v1
	v_cvt_pk_bf16_f32 v153, v2, v3
	v_add_u32_e32 v149, 0x58100, v147
	global_store_dwordx4 v149, v[150:153], s[10:11]
	s_andn2_b64 vcc, exec, s[4:5]
	s_mov_b64 s[4:5], -1
	s_cbranch_vccnz .LBB0_810
	s_andn2_b64 vcc, exec, s[6:7]
	s_cbranch_vccnz .LBB0_809
	s_barrier
	s_branch .LBB0_809

	.amdhsa_kernel _Z8mega_fwd6Params
		.amdhsa_group_segment_fixed_size 0
		.amdhsa_private_segment_fixed_size 0
		.amdhsa_kernarg_size 520
		.amdhsa_user_sgpr_count 2
		.amdhsa_user_sgpr_dispatch_ptr 0
		.amdhsa_user_sgpr_queue_ptr 0
		.amdhsa_user_sgpr_kernarg_segment_ptr 1
		.amdhsa_user_sgpr_dispatch_id 0
		.amdhsa_user_sgpr_kernarg_preload_length 0
		.amdhsa_user_sgpr_kernarg_preload_offset 0
		.amdhsa_user_sgpr_private_segment_size 0
		.amdhsa_uses_dynamic_stack 0
		.amdhsa_enable_private_segment 0
		.amdhsa_system_sgpr_workgroup_id_x 1
		.amdhsa_system_sgpr_workgroup_id_y 0
		.amdhsa_system_sgpr_workgroup_id_z 0
		.amdhsa_system_sgpr_workgroup_info 0
		.amdhsa_system_vgpr_workitem_id 2
		.amdhsa_next_free_vgpr 237
		.amdhsa_next_free_sgpr 102
		.amdhsa_accum_offset 240
		.amdhsa_reserve_vcc 1
		.amdhsa_float_round_mode_32 0
		.amdhsa_float_round_mode_16_64 0
		.amdhsa_float_denorm_mode_32 3
		.amdhsa_float_denorm_mode_16_64 3
		.amdhsa_dx10_clamp 1
		.amdhsa_ieee_mode 1
		.amdhsa_fp16_overflow 0
		.amdhsa_tg_split 0
		.amdhsa_exception_fp_ieee_invalid_op 0
		.amdhsa_exception_fp_denorm_src 0
		.amdhsa_exception_fp_ieee_div_zero 0
		.amdhsa_exception_fp_ieee_overflow 0
		.amdhsa_exception_fp_ieee_underflow 0
		.amdhsa_exception_fp_ieee_inexact 0
		.amdhsa_exception_int_div_zero 0
	.end_amdhsa_kernel

amdhsa.kernels:
  - .agpr_count:     0
    .args:
      - .offset:         0
        .size:           264
        .value_kind:     by_value
      - .offset:         264
        .size:           4
        .value_kind:     hidden_block_count_x
      - .offset:         268
        .size:           4
        .value_kind:     hidden_block_count_y
      - .offset:         272
        .size:           4
        .value_kind:     hidden_block_count_z
      - .offset:         276
        .size:           2
        .value_kind:     hidden_group_size_x
      - .offset:         278
        .size:           2
        .value_kind:     hidden_group_size_y
      - .offset:         280
        .size:           2
        .value_kind:     hidden_group_size_z
      - .offset:         282
        .size:           2
        .value_kind:     hidden_remainder_x
      - .offset:         284
        .size:           2
        .value_kind:     hidden_remainder_y
      - .offset:         286
        .size:           2
        .value_kind:     hidden_remainder_z
      - .offset:         304
        .size:           8
        .value_kind:     hidden_global_offset_x
      - .offset:         312
        .size:           8
        .value_kind:     hidden_global_offset_y
      - .offset:         320
        .size:           8
        .value_kind:     hidden_global_offset_z
      - .offset:         328
        .size:           2
        .value_kind:     hidden_grid_dims
      - .offset:         352
        .size:           8
        .value_kind:     hidden_multigrid_sync_arg
      - .offset:         384
        .size:           4
        .value_kind:     hidden_dynamic_lds_size
    .group_segment_fixed_size: 0
    .kernarg_segment_align: 8
    .kernarg_segment_size: 520
    .language:       OpenCL C
    .language_version:
      - 2
      - 0
    .max_flat_workgroup_size: 512
    .name:           _Z8mega_fwd6Params
    .private_segment_fixed_size: 0
    .sgpr_count:     108
    .sgpr_spill_count: 65
    .symbol:         _Z8mega_fwd6Params.kd
    .uniform_work_group_size: 1
    .uses_dynamic_stack: false
    .vgpr_count:     237
    .vgpr_spill_count: 0
    .wavefront_size: 64
